# poolfold d-loop: all 34 loads of an iteration issued before one wait (was 17 serial round trips), global_load instead of flat
# speedup vs baseline: 1.0288x; 1.0288x over previous
.LBB0_621:
	s_add_u32 s14, s8, s0
	s_addc_u32 s15, s18, s1
	v_mov_b64_e32 v[170:171], s[14:15]
	global_load_dword v96, v[170:171], off
	v_lshl_add_u64 v[170:171], v[28:29], 0, s[0:1]
	v_add_co_u32_e32 v170, vcc, s97, v170
	global_load_dword v27, v[80:81], off
	s_nop 0
	v_addc_co_u32_e32 v171, vcc, 0, v171, vcc
	global_load_dword v174, v[170:171], off
	global_load_dword v175, v[170:171], off offset:512
	v_lshl_add_u64 v[80:81], v[80:81], 0, s[20:21]
	global_load_dword v176, v[170:171], off offset:1024
	global_load_dword v177, v[170:171], off offset:1536
	global_load_dword v178, v[170:171], off offset:2048
	global_load_dword v179, v[170:171], off offset:2560
	global_load_dword v180, v[170:171], off offset:3072
	global_load_dword v181, v[170:171], off offset:3584
	v_lshl_add_u64 v[170:171], v[78:79], 0, s[0:1]
	global_load_dword v182, v[170:171], off
	v_lshl_add_u64 v[172:173], v[76:77], 0, s[0:1]
	global_load_dword v183, v[172:173], off
	v_lshl_add_u64 v[172:173], v[72:73], 0, s[0:1]
	v_lshl_add_u64 v[170:171], v[74:75], 0, s[0:1]
	global_load_dword v184, v[170:171], off
	s_nop 0
	global_load_dword v185, v[172:173], off
	v_lshl_add_u64 v[172:173], v[68:69], 0, s[0:1]
	v_lshl_add_u64 v[170:171], v[70:71], 0, s[0:1]
	global_load_dword v186, v[170:171], off
	s_nop 0
	global_load_dword v187, v[172:173], off
	v_lshl_add_u64 v[172:173], v[64:65], 0, s[0:1]
	v_lshl_add_u64 v[170:171], v[66:67], 0, s[0:1]
	global_load_dword v188, v[170:171], off
	s_nop 0
	global_load_dword v189, v[172:173], off
	v_lshl_add_u64 v[172:173], v[60:61], 0, s[0:1]
	v_lshl_add_u64 v[170:171], v[62:63], 0, s[0:1]
	global_load_dword v190, v[170:171], off
	s_nop 0
	global_load_dword v191, v[172:173], off
	v_lshl_add_u64 v[172:173], v[56:57], 0, s[0:1]
	v_lshl_add_u64 v[170:171], v[58:59], 0, s[0:1]
	global_load_dword v192, v[170:171], off
	s_nop 0
	global_load_dword v193, v[172:173], off
	v_lshl_add_u64 v[172:173], v[52:53], 0, s[0:1]
	v_lshl_add_u64 v[170:171], v[54:55], 0, s[0:1]
	global_load_dword v194, v[170:171], off
	s_nop 0
	global_load_dword v195, v[172:173], off
	v_lshl_add_u64 v[172:173], v[48:49], 0, s[0:1]
	v_lshl_add_u64 v[170:171], v[50:51], 0, s[0:1]
	global_load_dword v196, v[170:171], off
	s_nop 0
	global_load_dword v197, v[172:173], off
	v_lshl_add_u64 v[172:173], v[44:45], 0, s[0:1]
	v_lshl_add_u64 v[170:171], v[46:47], 0, s[0:1]
	global_load_dword v200, v[170:171], off
	s_nop 0
	global_load_dword v201, v[172:173], off
	v_lshl_add_u64 v[172:173], v[38:39], 0, s[0:1]
	v_lshl_add_u64 v[170:171], v[42:43], 0, s[0:1]
	global_load_dword v202, v[170:171], off
	s_nop 0
	global_load_dword v203, v[172:173], off
	v_lshl_add_u64 v[172:173], v[34:35], 0, s[0:1]
	v_lshl_add_u64 v[170:171], v[36:37], 0, s[0:1]
	global_load_dword v204, v[170:171], off
	s_nop 0
	global_load_dword v205, v[172:173], off
	v_lshl_add_u64 v[172:173], v[30:31], 0, s[0:1]
	v_lshl_add_u64 v[170:171], v[32:33], 0, s[0:1]
	global_load_dword v206, v[170:171], off
	s_add_u32 s0, s0, 4
	global_load_dword v207, v[172:173], off
	s_addc_u32 s1, s1, 0
	s_cmpk_lg_i32 s0, 0x100
	s_waitcnt vmcnt(0)
	v_mul_f32_e32 v96, v27, v96
	v_pk_fma_f32 v[82:83], v[96:97], v[174:175], v[82:83] op_sel_hi:[0,1,1]
	v_pk_fma_f32 v[86:87], v[96:97], v[176:177], v[86:87] op_sel_hi:[0,1,1]
	v_pk_fma_f32 v[84:85], v[96:97], v[178:179], v[84:85] op_sel_hi:[0,1,1]
	v_pk_fma_f32 v[90:91], v[96:97], v[180:181], v[90:91] op_sel_hi:[0,1,1]
	v_pk_fma_f32 v[88:89], v[96:97], v[182:183], v[88:89] op_sel_hi:[0,1,1]
	v_pk_fma_f32 v[94:95], v[96:97], v[184:185], v[94:95] op_sel_hi:[0,1,1]
	v_pk_fma_f32 v[92:93], v[96:97], v[186:187], v[92:93] op_sel_hi:[0,1,1]
	v_pk_fma_f32 v[100:101], v[96:97], v[188:189], v[100:101] op_sel_hi:[0,1,1]
	v_pk_fma_f32 v[98:99], v[96:97], v[190:191], v[98:99] op_sel_hi:[0,1,1]
	v_pk_fma_f32 v[104:105], v[96:97], v[192:193], v[104:105] op_sel_hi:[0,1,1]
	v_pk_fma_f32 v[102:103], v[96:97], v[194:195], v[102:103] op_sel_hi:[0,1,1]
	v_pk_fma_f32 v[108:109], v[96:97], v[196:197], v[108:109] op_sel_hi:[0,1,1]
	v_pk_fma_f32 v[106:107], v[96:97], v[200:201], v[106:107] op_sel_hi:[0,1,1]
	v_pk_fma_f32 v[112:113], v[96:97], v[202:203], v[112:113] op_sel_hi:[0,1,1]
	v_pk_fma_f32 v[110:111], v[96:97], v[204:205], v[110:111] op_sel_hi:[0,1,1]
	v_pk_fma_f32 v[40:41], v[96:97], v[206:207], v[40:41] op_sel_hi:[0,1,1]
	s_cbranch_scc1 .LBB0_621
	v_add_u32_e32 v27, 0x400, v114
	ds_write2_b32 v114, v82, v83 offset1:66
	ds_write2_b32 v114, v86, v87 offset0:132 offset1:198
	ds_write2_b32 v27, v84, v85 offset0:8 offset1:74
	ds_write2_b32 v27, v90, v91 offset0:140 offset1:206
	v_add_u32_e32 v27, 0x800, v114
	ds_write2_b32 v27, v88, v89 offset0:16 offset1:82
	ds_write2_b32 v27, v94, v95 offset0:148 offset1:214
	v_add_u32_e32 v27, 0xc00, v114
	ds_write2_b32 v27, v92, v93 offset0:24 offset1:90
	ds_write2_b32 v27, v100, v101 offset0:156 offset1:222
	v_add_u32_e32 v27, 0x1000, v114
	ds_write2_b32 v27, v98, v99 offset0:32 offset1:98
	ds_write2_b32 v27, v104, v105 offset0:164 offset1:230
	v_add_u32_e32 v27, 0x1400, v114
	ds_write2_b32 v27, v102, v103 offset0:40 offset1:106
	ds_write2_b32 v27, v108, v109 offset0:172 offset1:238
	v_add_u32_e32 v27, 0x1800, v114
	ds_write2_b32 v27, v106, v107 offset0:48 offset1:114
	ds_write2_b32 v27, v112, v113 offset0:180 offset1:246
	v_add_u32_e32 v27, 0x1c00, v114
	ds_write2_b32 v27, v110, v111 offset0:56 offset1:122
	ds_write2_b32 v27, v40, v41 offset0:188 offset1:254
	s_waitcnt lgkmcnt(0)
	s_add_i32 s0, s78, 0xffffd000
	ds_read2_b32 v[28:29], v116 offset1:33
	s_lshl_b32 s1, s0, 5
	s_waitcnt lgkmcnt(0)
	v_cvt_pk_bf16_f32 v28, v28, v29
	ds_read2_b32 v[30:31], v116 offset0:66 offset1:99
	s_and_b32 s1, s1, 0x3e0
	s_waitcnt lgkmcnt(0)
	v_cvt_pk_bf16_f32 v29, v30, v31
	ds_read2_b32 v[30:31], v116 offset0:132 offset1:165
	v_or_b32_e32 v27, s1, v115
	s_waitcnt lgkmcnt(0)
	v_cvt_pk_bf16_f32 v30, v30, v31
	ds_read2_b32 v[32:33], v116 offset0:198 offset1:231
	v_lshlrev_b32_e32 v96, 11, v27
	s_lshl_b32 s0, s0, 2
	s_waitcnt lgkmcnt(0)
	v_cvt_pk_bf16_f32 v31, v32, v33
	v_lshl_add_u64 v[32:33], s[6:7], 0, v[96:97]
	s_and_b32 s16, s0, 0x180
	v_lshl_add_u64 v[32:33], v[32:33], 0, s[16:17]
	v_mov_b32_e32 v27, v97
	v_lshl_add_u64 v[32:33], v[32:33], 0, v[26:27]
	ds_read2_b32 v[34:35], v116 offset0:8 offset1:41
	global_store_dwordx4 v[32:33], v[28:31], off offset:1024
	s_waitcnt lgkmcnt(0)
	s_nop 0
	v_cvt_pk_bf16_f32 v28, v34, v35
	ds_read2_b32 v[30:31], v116 offset0:74 offset1:107
	s_waitcnt lgkmcnt(0)
	v_cvt_pk_bf16_f32 v29, v30, v31
	ds_read2_b32 v[30:31], v116 offset0:140 offset1:173
	s_waitcnt lgkmcnt(0)
	v_cvt_pk_bf16_f32 v30, v30, v31
	ds_read2_b32 v[32:33], v116 offset0:206 offset1:239
	s_waitcnt lgkmcnt(0)
	v_cvt_pk_bf16_f32 v31, v32, v33
	v_or_b32_e32 v32, s1, v117
	v_lshlrev_b32_e32 v96, 11, v32
	v_lshl_add_u64 v[34:35], s[6:7], 0, v[96:97]
	v_lshl_add_u64 v[34:35], v[34:35], 0, s[16:17]
	v_lshl_add_u64 v[34:35], v[34:35], 0, v[26:27]
	ds_read2_b32 v[32:33], v116 offset0:16 offset1:49
	global_store_dwordx4 v[34:35], v[28:31], off offset:1024
	s_waitcnt lgkmcnt(0)
	s_nop 0
	v_cvt_pk_bf16_f32 v28, v32, v33
	ds_read2_b32 v[30:31], v116 offset0:82 offset1:115
	s_waitcnt lgkmcnt(0)
	v_cvt_pk_bf16_f32 v29, v30, v31
	ds_read2_b32 v[30:31], v116 offset0:148 offset1:181
	s_waitcnt lgkmcnt(0)
	v_cvt_pk_bf16_f32 v30, v30, v31
	ds_read2_b32 v[32:33], v116 offset0:214 offset1:247
	s_waitcnt lgkmcnt(0)
	v_cvt_pk_bf16_f32 v31, v32, v33
	v_or_b32_e32 v32, s1, v118
	v_lshlrev_b32_e32 v96, 11, v32
	v_lshl_add_u64 v[34:35], s[6:7], 0, v[96:97]
	v_lshl_add_u64 v[34:35], v[34:35], 0, s[16:17]
	v_lshl_add_u64 v[34:35], v[34:35], 0, v[26:27]
	ds_read2_b32 v[32:33], v116 offset0:24 offset1:57
	global_store_dwordx4 v[34:35], v[28:31], off offset:1024
	s_waitcnt lgkmcnt(0)
	s_nop 0
	v_cvt_pk_bf16_f32 v28, v32, v33
	ds_read2_b32 v[30:31], v116 offset0:90 offset1:123
	s_waitcnt lgkmcnt(0)
	v_cvt_pk_bf16_f32 v29, v30, v31
	ds_read2_b32 v[30:31], v116 offset0:156 offset1:189
	s_waitcnt lgkmcnt(0)
	v_cvt_pk_bf16_f32 v30, v30, v31
	v_or_b32_e32 v31, s1, v119
	v_lshlrev_b32_e32 v96, 11, v31
	v_lshl_add_u64 v[34:35], s[6:7], 0, v[96:97]
	ds_read2_b32 v[32:33], v116 offset0:222 offset1:255
	v_lshl_add_u64 v[34:35], v[34:35], 0, s[16:17]
	s_waitcnt lgkmcnt(0)
	v_cvt_pk_bf16_f32 v31, v32, v33
	v_lshl_add_u64 v[32:33], v[34:35], 0, v[26:27]
	global_store_dwordx4 v[32:33], v[28:31], off offset:1024
	s_waitcnt lgkmcnt(0)
	s_mov_b64 s[0:1], 0

.LBB0_1050:
	s_add_u32 s14, s6, s0
	s_addc_u32 s15, s7, s1
	v_mov_b64_e32 v[170:171], s[14:15]
	global_load_dword v25, v[80:81], off
	global_load_dword v96, v[170:171], off
	v_lshl_add_u64 v[170:171], v[28:29], 0, s[0:1]
	global_load_dword v174, v[170:171], off
	global_load_dword v175, v[170:171], off offset:512
	v_lshl_add_u64 v[80:81], v[80:81], 0, s[58:59]
	global_load_dword v176, v[170:171], off offset:1024
	global_load_dword v177, v[170:171], off offset:1536
	global_load_dword v178, v[170:171], off offset:2048
	global_load_dword v179, v[170:171], off offset:2560
	global_load_dword v180, v[170:171], off offset:3072
	global_load_dword v181, v[170:171], off offset:3584
	v_lshl_add_u64 v[170:171], v[78:79], 0, s[0:1]
	global_load_dword v182, v[170:171], off
	v_lshl_add_u64 v[172:173], v[76:77], 0, s[0:1]
	global_load_dword v183, v[172:173], off
	v_lshl_add_u64 v[172:173], v[72:73], 0, s[0:1]
	v_lshl_add_u64 v[170:171], v[74:75], 0, s[0:1]
	global_load_dword v184, v[170:171], off
	s_nop 0
	global_load_dword v185, v[172:173], off
	v_lshl_add_u64 v[172:173], v[68:69], 0, s[0:1]
	v_lshl_add_u64 v[170:171], v[70:71], 0, s[0:1]
	global_load_dword v186, v[170:171], off
	s_nop 0
	global_load_dword v187, v[172:173], off
	v_lshl_add_u64 v[172:173], v[64:65], 0, s[0:1]
	v_lshl_add_u64 v[170:171], v[66:67], 0, s[0:1]
	global_load_dword v188, v[170:171], off
	s_nop 0
	global_load_dword v189, v[172:173], off
	v_lshl_add_u64 v[172:173], v[60:61], 0, s[0:1]
	v_lshl_add_u64 v[170:171], v[62:63], 0, s[0:1]
	global_load_dword v190, v[170:171], off
	s_nop 0
	global_load_dword v191, v[172:173], off
	v_lshl_add_u64 v[172:173], v[56:57], 0, s[0:1]
	v_lshl_add_u64 v[170:171], v[58:59], 0, s[0:1]
	global_load_dword v192, v[170:171], off
	s_nop 0
	global_load_dword v193, v[172:173], off
	v_lshl_add_u64 v[172:173], v[52:53], 0, s[0:1]
	v_lshl_add_u64 v[170:171], v[54:55], 0, s[0:1]
	global_load_dword v194, v[170:171], off
	s_nop 0
	global_load_dword v195, v[172:173], off
	v_lshl_add_u64 v[172:173], v[48:49], 0, s[0:1]
	v_lshl_add_u64 v[170:171], v[50:51], 0, s[0:1]
	global_load_dword v196, v[170:171], off
	s_nop 0
	global_load_dword v197, v[172:173], off
	v_lshl_add_u64 v[172:173], v[44:45], 0, s[0:1]
	v_lshl_add_u64 v[170:171], v[46:47], 0, s[0:1]
	global_load_dword v200, v[170:171], off
	s_nop 0
	global_load_dword v201, v[172:173], off
	v_lshl_add_u64 v[172:173], v[40:41], 0, s[0:1]
	v_lshl_add_u64 v[170:171], v[42:43], 0, s[0:1]
	global_load_dword v202, v[170:171], off
	s_nop 0
	global_load_dword v203, v[172:173], off
	v_lshl_add_u64 v[172:173], v[36:37], 0, s[0:1]
	v_lshl_add_u64 v[170:171], v[38:39], 0, s[0:1]
	global_load_dword v204, v[170:171], off
	s_nop 0
	global_load_dword v205, v[172:173], off
	v_lshl_add_u64 v[172:173], v[30:31], 0, s[0:1]
	v_lshl_add_u64 v[170:171], v[32:33], 0, s[0:1]
	global_load_dword v206, v[170:171], off
	s_add_u32 s0, s0, 4
	global_load_dword v207, v[172:173], off
	s_addc_u32 s1, s1, 0
	s_cmpk_lg_i32 s0, 0x100
	s_waitcnt vmcnt(0)
	v_mul_f32_e32 v96, v25, v96
	v_pk_fma_f32 v[82:83], v[96:97], v[174:175], v[82:83] op_sel_hi:[0,1,1]
	v_pk_fma_f32 v[86:87], v[96:97], v[176:177], v[86:87] op_sel_hi:[0,1,1]
	v_pk_fma_f32 v[84:85], v[96:97], v[178:179], v[84:85] op_sel_hi:[0,1,1]
	v_pk_fma_f32 v[90:91], v[96:97], v[180:181], v[90:91] op_sel_hi:[0,1,1]
	v_pk_fma_f32 v[88:89], v[96:97], v[182:183], v[88:89] op_sel_hi:[0,1,1]
	v_pk_fma_f32 v[94:95], v[96:97], v[184:185], v[94:95] op_sel_hi:[0,1,1]
	v_pk_fma_f32 v[92:93], v[96:97], v[186:187], v[92:93] op_sel_hi:[0,1,1]
	v_pk_fma_f32 v[100:101], v[96:97], v[188:189], v[100:101] op_sel_hi:[0,1,1]
	v_pk_fma_f32 v[98:99], v[96:97], v[190:191], v[98:99] op_sel_hi:[0,1,1]
	v_pk_fma_f32 v[104:105], v[96:97], v[192:193], v[104:105] op_sel_hi:[0,1,1]
	v_pk_fma_f32 v[102:103], v[96:97], v[194:195], v[102:103] op_sel_hi:[0,1,1]
	v_pk_fma_f32 v[108:109], v[96:97], v[196:197], v[108:109] op_sel_hi:[0,1,1]
	v_pk_fma_f32 v[106:107], v[96:97], v[200:201], v[106:107] op_sel_hi:[0,1,1]
	v_pk_fma_f32 v[112:113], v[96:97], v[202:203], v[112:113] op_sel_hi:[0,1,1]
	v_pk_fma_f32 v[110:111], v[96:97], v[204:205], v[110:111] op_sel_hi:[0,1,1]
	v_pk_fma_f32 v[34:35], v[96:97], v[206:207], v[34:35] op_sel_hi:[0,1,1]
	s_cbranch_scc1 .LBB0_1050
	v_add_u32_e32 v25, 0x400, v114
	ds_write2_b32 v114, v82, v83 offset1:66
	ds_write2_b32 v114, v86, v87 offset0:132 offset1:198
	ds_write2_b32 v25, v84, v85 offset0:8 offset1:74
	ds_write2_b32 v25, v90, v91 offset0:140 offset1:206
	v_add_u32_e32 v25, 0x800, v114
	ds_write2_b32 v25, v88, v89 offset0:16 offset1:82
	ds_write2_b32 v25, v94, v95 offset0:148 offset1:214
	v_add_u32_e32 v25, 0xc00, v114
	ds_write2_b32 v25, v92, v93 offset0:24 offset1:90
	ds_write2_b32 v25, v100, v101 offset0:156 offset1:222
	v_add_u32_e32 v25, 0x1000, v114
	ds_write2_b32 v25, v98, v99 offset0:32 offset1:98
	ds_write2_b32 v25, v104, v105 offset0:164 offset1:230
	v_add_u32_e32 v25, 0x1400, v114
	ds_write2_b32 v25, v102, v103 offset0:40 offset1:106
	ds_write2_b32 v25, v108, v109 offset0:172 offset1:238
	v_add_u32_e32 v25, 0x1800, v114
	ds_write2_b32 v25, v106, v107 offset0:48 offset1:114
	ds_write2_b32 v25, v112, v113 offset0:180 offset1:246
	v_add_u32_e32 v25, 0x1c00, v114
	ds_write2_b32 v25, v110, v111 offset0:56 offset1:122
	ds_write2_b32 v25, v34, v35 offset0:188 offset1:254
	s_waitcnt lgkmcnt(0)
	s_add_i32 s0, s46, 0xffffd000
	ds_read2_b32 v[28:29], v116 offset1:33
	s_lshl_b32 s1, s0, 5
	s_waitcnt lgkmcnt(0)
	v_cvt_pk_bf16_f32 v28, v28, v29
	ds_read2_b32 v[30:31], v116 offset0:66 offset1:99
	s_and_b32 s1, s1, 0x3e0
	s_waitcnt lgkmcnt(0)
	v_cvt_pk_bf16_f32 v29, v30, v31
	ds_read2_b32 v[30:31], v116 offset0:132 offset1:165
	v_or_b32_e32 v25, s1, v115
	s_waitcnt lgkmcnt(0)
	v_cvt_pk_bf16_f32 v30, v30, v31
	ds_read2_b32 v[32:33], v116 offset0:198 offset1:231
	v_lshlrev_b32_e32 v96, 11, v25
	s_lshl_b32 s0, s0, 2
	s_waitcnt lgkmcnt(0)
	v_cvt_pk_bf16_f32 v31, v32, v33
	v_lshl_add_u64 v[32:33], s[4:5], 0, v[96:97]
	s_and_b32 s16, s0, 0x180
	v_lshl_add_u64 v[32:33], v[32:33], 0, s[16:17]
	v_mov_b32_e32 v25, v97
	v_lshl_add_u64 v[32:33], v[32:33], 0, v[24:25]
	ds_read2_b32 v[34:35], v116 offset0:8 offset1:41
	global_store_dwordx4 v[32:33], v[28:31], off offset:1024
	s_waitcnt lgkmcnt(0)
	s_nop 0
	v_cvt_pk_bf16_f32 v28, v34, v35
	ds_read2_b32 v[30:31], v116 offset0:74 offset1:107
	s_waitcnt lgkmcnt(0)
	v_cvt_pk_bf16_f32 v29, v30, v31
	ds_read2_b32 v[30:31], v116 offset0:140 offset1:173
	s_waitcnt lgkmcnt(0)
	v_cvt_pk_bf16_f32 v30, v30, v31
	ds_read2_b32 v[32:33], v116 offset0:206 offset1:239
	s_waitcnt lgkmcnt(0)
	v_cvt_pk_bf16_f32 v31, v32, v33
	v_or_b32_e32 v32, s1, v117
	v_lshlrev_b32_e32 v96, 11, v32
	v_lshl_add_u64 v[34:35], s[4:5], 0, v[96:97]
	v_lshl_add_u64 v[34:35], v[34:35], 0, s[16:17]
	v_lshl_add_u64 v[34:35], v[34:35], 0, v[24:25]
	ds_read2_b32 v[32:33], v116 offset0:16 offset1:49
	global_store_dwordx4 v[34:35], v[28:31], off offset:1024
	s_waitcnt lgkmcnt(0)
	s_nop 0
	v_cvt_pk_bf16_f32 v28, v32, v33
	ds_read2_b32 v[30:31], v116 offset0:82 offset1:115
	s_waitcnt lgkmcnt(0)
	v_cvt_pk_bf16_f32 v29, v30, v31
	ds_read2_b32 v[30:31], v116 offset0:148 offset1:181
	s_waitcnt lgkmcnt(0)
	v_cvt_pk_bf16_f32 v30, v30, v31
	ds_read2_b32 v[32:33], v116 offset0:214 offset1:247
	s_waitcnt lgkmcnt(0)
	v_cvt_pk_bf16_f32 v31, v32, v33
	v_or_b32_e32 v32, s1, v118
	v_lshlrev_b32_e32 v96, 11, v32
	v_lshl_add_u64 v[34:35], s[4:5], 0, v[96:97]
	v_lshl_add_u64 v[34:35], v[34:35], 0, s[16:17]
	v_lshl_add_u64 v[34:35], v[34:35], 0, v[24:25]
	ds_read2_b32 v[32:33], v116 offset0:24 offset1:57
	global_store_dwordx4 v[34:35], v[28:31], off offset:1024
	s_waitcnt lgkmcnt(0)
	s_nop 0
	v_cvt_pk_bf16_f32 v28, v32, v33
	ds_read2_b32 v[30:31], v116 offset0:90 offset1:123
	s_waitcnt lgkmcnt(0)
	v_cvt_pk_bf16_f32 v29, v30, v31
	ds_read2_b32 v[30:31], v116 offset0:156 offset1:189
	s_waitcnt lgkmcnt(0)
	v_cvt_pk_bf16_f32 v30, v30, v31
	v_or_b32_e32 v31, s1, v119
	v_lshlrev_b32_e32 v96, 11, v31
	v_lshl_add_u64 v[34:35], s[4:5], 0, v[96:97]
	ds_read2_b32 v[32:33], v116 offset0:222 offset1:255
	v_lshl_add_u64 v[34:35], v[34:35], 0, s[16:17]
	s_waitcnt lgkmcnt(0)
	v_cvt_pk_bf16_f32 v31, v32, v33
	v_lshl_add_u64 v[32:33], v[34:35], 0, v[24:25]
	global_store_dwordx4 v[32:33], v[28:31], off offset:1024
	s_waitcnt lgkmcnt(0)
	s_mov_b64 s[0:1], 0
